# v91 + GDN scan step: the last seven next-step operand loads moved from the first half into the second half's MFMA blocks (same order among vector-memory operations)
# speedup vs baseline: 1.0048x; 1.0048x over previous
; __device__ __forceinline__ void chain_load(ChainOps& o, const GdnP& P, int b, int h, int n, int w, int mt, int nh, int lane, int tid) {
;     const int l15 = lane & 15, quad = lane >> 4;
;     const int cn = b * 64 + n, unit = cn * 8 + h, row0 = cn * 64;
;     const bf16_t* wrow = P.wbuf + (size_t)unit * 8192 + (mt * 16 + l15) * 128 + quad * 8;
;     const bf16_t* qrow = P.proj + (size_t)(row0 + mt * 16 + l15) * NIN + C_GDN + h * 128 + quad * 8;
; #pragma unroll
;     for (int s = 0; s < 4; ++s) { o.wf[s] = *(const bf16x8*)(wrow + 32 * s); o.qf[s] = *(const bf16x8*)(qrow + 32 * s); }
;     const bf16_t* arow = P.attnb + (size_t)unit * 4096 + (mt * 16 + l15) * 64 + quad * 8;
;     const int kidx = w * 16 + l15;
;     const bf16_t* krow = P.proj + (size_t)(row0 + (kidx >> 1)) * NIN + C_GDN + 1024 + h * 128 + (kidx & 1) * 64 + quad * 8;
; #pragma unroll
;     for (int s = 0; s < 2; ++s) { o.af[s] = *(const bf16x8*)(arow + 32 * s); o.kf[s] = *(const bf16x8*)(krow + 32 * s); }
;     o.cd = P.cdb[unit];
;     const int cb = ((mt * 2 + nh) * 64 + lane) * 2;
;     const bf16_t* up = P.proj + (size_t)(row0 + (cb >> 4)) * NIN + C_GDN + 2048 + h * 128 + (cb & 15) * 8;
;     o.uf[0] = *(const u32x4*)up; o.uf[1] = *(const u32x4*)(up + 8);
; __device__ __forceinline__ void gdn_chain(LAS unsigned char* lds, const GdnP& P, const float* out_norm, int bh, const int tid) {
;     ...
;     for (int n = 0; n < 64; ++n) {
;         const int row0 = (b * 64 + n) * 64;
;         chain_load(nxt, P, b, h, n < 63 ? n + 1 : n, w, mt, nh, lane, tid);
;         f32x4 oacc[4];
; #pragma unroll
;         for (int q = 0; q < 4; ++q) { const int nt = 4 * nh + q; f32x4 a1 = (f32x4){0.f, 0.f, 0.f, 0.f}; oacc[q] = (f32x4){0.f, 0.f, 0.f, 0.f};
; #pragma unroll
;             for (int s = 0; s < 4; ++s) { const bf16x8 sf = *(const LAS bf16x8*)(lds + GC_ST + (nt * 16 + l15) * 272 + (quad * 8 + 32 * s) * 2);
;                 a1 = __builtin_amdgcn_mfma_f32_16x16x32_bf16(cur.wf[s], sf, a1, 0, 0, 0); oacc[q] = __builtin_amdgcn_mfma_f32_16x16x32_bf16(cur.qf[s], sf, oacc[q], 0, 0, 0); }
;             const unsigned u01 = cur.uf[q >> 1][(q & 1) * 2], u23 = cur.uf[q >> 1][(q & 1) * 2 + 1];
;             u32x2 pv; pv.x = pk2(bflo(u01) - a1[0], bfhi(u01) - a1[1]); pv.y = pk2(bflo(u23) - a1[2], bfhi(u23) - a1[3]);
;             *(LAS u32x2*)(lds + GC_VT + (nt * 16 + l15) * 144 + (mt * 16 + quad * 4) * 2) = pv; }
.LBB0_1126:
	s_waitcnt vmcnt(14)
	v_mov_b64_e32 v[90:91], v[74:75]
	v_mov_b64_e32 v[88:89], v[72:73]
	ds_read_b128 v[72:75], v161
	ds_read_b128 v[92:95], v161 offset:64
	s_waitcnt vmcnt(13)
	v_mov_b64_e32 v[106:107], v[14:15]
	v_mov_b64_e32 v[104:105], v[12:13]
	s_waitcnt vmcnt(10)
	v_mov_b64_e32 v[110:111], v[22:23]
	s_waitcnt lgkmcnt(1)
	v_mfma_f32_16x16x32_bf16 v[96:99], v[88:91], v[72:75], 0
	s_waitcnt vmcnt(8)
	v_mov_b64_e32 v[102:103], v[30:31]
	v_mov_b64_e32 v[108:109], v[20:21]
	ds_read_b128 v[20:23], v161 offset:128
	v_mov_b64_e32 v[100:101], v[28:29]
	s_waitcnt lgkmcnt(1)
	v_mfma_f32_16x16x32_bf16 v[28:31], v[104:107], v[92:95], v[96:99]
	v_mov_b64_e32 v[180:181], v[18:19]
	v_mov_b64_e32 v[184:185], v[6:7]
	v_mov_b64_e32 v[178:179], v[16:17]
	v_mov_b64_e32 v[182:183], v[4:5]
	ds_read_b128 v[4:7], v161 offset:192
	s_waitcnt lgkmcnt(1)
	v_mfma_f32_16x16x32_bf16 v[16:19], v[108:111], v[20:23], v[28:31]
	v_mov_b64_e32 v[188:189], v[2:3]
	v_mov_b64_e32 v[186:187], v[0:1]
	s_waitcnt vmcnt(7)
	v_mov_b64_e32 v[192:193], v[10:11]
	v_mfma_f32_16x16x32_bf16 v[12:15], v[100:103], v[72:75], 0
	v_mov_b64_e32 v[190:191], v[8:9]
	s_waitcnt vmcnt(3)
	v_lshlrev_b32_e32 v8, 16, v80
	v_and_b32_e32 v9, 0xffff0000, v80
	s_waitcnt lgkmcnt(0)
	v_mfma_f32_16x16x32_bf16 v[0:3], v[178:181], v[4:7], v[16:19]
	s_add_i32 s0, s47, 0x41
	s_cmp_lg_u32 s47, -1
	s_cselect_b32 s0, s0, 63
	s_add_i32 s0, s0, s44
	s_lshl_b32 s30, s0, 3
	s_nop 2
	v_pk_add_f32 v[0:1], v[8:9], v[0:1] neg_lo:[0,1] neg_hi:[0,1]
	v_mfma_f32_16x16x32_bf16 v[8:11], v[182:185], v[92:95], v[12:15]
	v_cvt_pk_bf16_f32 v0, v0, v1
	s_or_b32 s30, s30, s43
	s_lshl_b32 s50, s0, 6
	v_lshlrev_b32_e32 v12, 16, v81
	v_and_b32_e32 v13, 0xffff0000, v81
	v_pk_add_f32 v[2:3], v[12:13], v[2:3] neg_lo:[0,1] neg_hi:[0,1]
	v_mfma_f32_16x16x32_bf16 v[8:11], v[186:189], v[20:23], v[8:11]
	v_cvt_pk_bf16_f32 v1, v2, v3
	v_add_u32_e32 v2, v155, v156
	ds_write_b64 v2, v[0:1] offset:34816
	ds_read_b128 v[0:3], v162
	v_mfma_f32_16x16x32_bf16 v[198:201], v[190:193], v[4:7], v[8:11]
	ds_read_b128 v[4:7], v162 offset:64
	ds_read_b128 v[12:15], v162 offset:128
	s_ashr_i32 s31, s30, 31
	s_waitcnt lgkmcnt(2)
	v_mfma_f32_16x16x32_bf16 v[8:11], v[88:91], v[0:3], 0
	v_mov_b64_e32 v[94:95], v[38:39]
	s_lshl_b64 s[48:49], s[30:31], 14
	v_or_b32_e32 v18, s50, v152
	v_mfma_f32_16x16x32_bf16 v[0:3], v[100:103], v[0:3], 0
	v_mov_b64_e32 v[202:203], s[16:17]
	v_mov_b64_e32 v[92:93], v[36:37]
	v_lshl_add_u64 v[16:17], v[132:133], 0, s[48:49]
	s_waitcnt lgkmcnt(1)
	v_mfma_f32_16x16x32_bf16 v[8:11], v[104:107], v[4:7], v[8:11]
	s_lshl_b32 s0, s45, 1
	v_mov_b64_e32 v[196:197], v[70:71]
	v_mov_b64_e32 v[194:195], v[68:69]
	v_mfma_f32_16x16x32_bf16 v[0:3], v[182:185], v[4:7], v[0:3]
	ds_read_b128 v[4:7], v162 offset:192
	v_mov_b64_e32 v[208:209], v[46:47]
	v_mov_b64_e32 v[98:99], v[50:51]
	s_waitcnt lgkmcnt(1)
	v_mfma_f32_16x16x32_bf16 v[8:11], v[108:111], v[12:15], v[8:11]
	v_mov_b64_e32 v[206:207], v[44:45]
	v_mov_b64_e32 v[96:97], v[48:49]
	v_add_u32_e32 v80, s50, v153
	s_waitcnt lgkmcnt(0)
	v_mfma_f32_16x16x32_bf16 v[8:11], v[178:181], v[4:7], v[8:11]
	v_mov_b32_e32 v138, v123
	v_mov_b32_e32 v123, v115
	v_mov_b32_e32 v127, v115
	v_mfma_f32_16x16x32_bf16 v[0:3], v[186:189], v[12:15], v[0:3]
	v_lshlrev_b32_e32 v14, 16, v82
	v_and_b32_e32 v15, 0xffff0000, v82
	s_nop 1
	v_pk_add_f32 v[8:9], v[14:15], v[8:9] neg_lo:[0,1] neg_hi:[0,1]
	v_lshlrev_b32_e32 v14, 16, v83
	v_and_b32_e32 v15, 0xffff0000, v83
	v_pk_add_f32 v[10:11], v[14:15], v[10:11] neg_lo:[0,1] neg_hi:[0,1]
	v_cvt_pk_bf16_f32 v8, v8, v9
	v_cvt_pk_bf16_f32 v9, v10, v11
	v_add_u32_e32 v10, v155, v157
	ds_write_b64 v10, v[8:9] offset:34816
	ds_read_b128 v[8:11], v163
	ds_read_b128 v[36:39], v163 offset:64
	v_mad_i64_i32 v[12:13], s[48:49], v18, s40, v[202:203]
	v_lshl_add_u64 v[12:13], v[12:13], 0, s[0:1]
	s_waitcnt lgkmcnt(1)
	v_mfma_f32_16x16x32_bf16 v[28:31], v[88:91], v[8:11], 0
	s_lshl_b64 s[48:49], s[30:31], 13
	v_lshl_add_u64 v[218:219], v[134:135], 0, s[48:49]
	v_mad_i64_i32 v[80:81], s[48:49], v80, s40, v[202:203]
	v_mfma_f32_16x16x32_bf16 v[210:213], v[190:193], v[4:7], v[0:3]
	s_lshl_b64 s[30:31], s[30:31], 2
	s_add_u32 s30, s2, s30
	s_addc_u32 s31, s3, s31
	v_lshl_add_u64 v[0:1], v[12:13], 0, v[114:115]
	v_add_co_u32_e32 v70, vcc, s41, v0
	v_lshl_add_u64 v[68:69], v[0:1], 0, s[22:23]
	s_nop 0
	v_addc_co_u32_e32 v71, vcc, 0, v1, vcc
	global_load_dwordx4 v[72:75], v[16:17], off
	global_load_dwordx4 v[12:15], v[16:17], off offset:64
	v_mfma_f32_16x16x32_bf16 v[44:47], v[100:103], v[8:11], 0
	global_load_dwordx4 v[4:7], v[68:69], off offset:64
	global_load_dwordx4 v[0:3], v[68:69], off offset:128
	global_load_dwordx4 v[20:23], v[16:17], off offset:128
	s_nop 0
	global_load_dwordx4 v[16:19], v[16:17], off offset:192
	v_pk_mul_f32 v[66:67], v[66:67], v[138:139] op_sel_hi:[1,0]
	v_pk_mul_f32 v[64:65], v[64:65], v[138:139] op_sel_hi:[1,0]
	s_waitcnt lgkmcnt(0)
	v_mfma_f32_16x16x32_bf16 v[48:51], v[104:107], v[36:39], v[28:31]
	s_nop 2
	global_load_dwordx4 v[28:31], v[70:71], off offset:2048
	global_load_dwordx4 v[8:11], v[68:69], off offset:192
	ds_read_b128 v[68:71], v163 offset:128
	v_pk_mul_f32 v[62:63], v[62:63], v[138:139] op_sel_hi:[1,0]
	v_mfma_f32_16x16x32_bf16 v[36:39], v[182:185], v[36:39], v[44:47]
	v_mul_f32_e64 v60, v60, v138
	v_mul_f32_e64 v61, v61, v138
	v_pk_mul_f32 v[58:59], v[58:59], v[138:139] op_sel_hi:[1,0]
	v_pk_mul_f32 v[56:57], v[56:57], v[138:139] op_sel_hi:[1,0]
	ds_read_b128 v[44:47], v163 offset:192
	s_waitcnt lgkmcnt(1)
; #define LAS __attribute__((address_space(3)))
; __device__ __forceinline__ unsigned f2bf(float f) { return pk2(f, 0.f) & 0xffffu; }
; __device__ __forceinline__ void chain_load(ChainOps& o, const GdnP& P, int b, int h, int n, int w, int mt, int nh, int lane, int tid) {
;     ...
;     for (int s = 0; s < 4; ++s) { o.wf[s] = *(const bf16x8*)(wrow + 32 * s); o.qf[s] = *(const bf16x8*)(qrow + 32 * s); }
;     const bf16_t* arow = P.attnb + (size_t)unit * 4096 + (mt * 16 + l15) * 64 + quad * 8;
;     const int kidx = w * 16 + l15;
;     const bf16_t* krow = P.proj + (size_t)(row0 + (kidx >> 1)) * NIN + C_GDN + 1024 + h * 128 + (kidx & 1) * 64 + quad * 8;
; #pragma unroll
;     for (int s = 0; s < 2; ++s) { o.af[s] = *(const bf16x8*)(arow + 32 * s); o.kf[s] = *(const bf16x8*)(krow + 32 * s); }
;     o.cd = P.cdb[unit];
;     const int cb = ((mt * 2 + nh) * 64 + lane) * 2;
;     const bf16_t* up = P.proj + (size_t)(row0 + (cb >> 4)) * NIN + C_GDN + 2048 + h * 128 + (cb & 15) * 8;
;     o.uf[0] = *(const u32x4*)up; o.uf[1] = *(const u32x4*)(up + 8);
; __device__ __forceinline__ void gdn_chain(LAS unsigned char* lds, const GdnP& P, const float* out_norm, int bh, const int tid) {
;     ...
;         lds_barrier();
;         float ss[4] = {0.f, 0.f, 0.f, 0.f};
; #pragma unroll
;         for (int q = 0; q < 4; ++q) { const int nt = 4 * nh + q;
; #pragma unroll
;             for (int s = 0; s < 2; ++s) { const bf16x8 vf = *(const LAS bf16x8*)(lds + GC_VT + (nt * 16 + l15) * 144 + (quad * 8 + 32 * s) * 2); oacc[q] = __builtin_amdgcn_mfma_f32_16x16x32_bf16(cur.af[s], vf, oacc[q], 0, 0, 0); }
; #pragma unroll
;             for (int i = 0; i < 4; ++i) { ss[i] += oacc[q][i] * oacc[q][i]; *(LAS bf16_t*)(lds + GC_OB + (mt * 16 + quad * 4 + i) * 272 + (nt * 16 + l15) * 2) = (bf16_t)f2bf(oacc[q][i]); } }
; #pragma unroll
;         for (int nt = 0; nt < 8; ++nt) { sacc[nt] = sacc[nt] * cur.cd;
; #pragma unroll
;             for (int s = 0; s < 2; ++s) { const bf16x8 vf = *(const LAS bf16x8*)(lds + GC_VT + (nt * 16 + l15) * 144 + (quad * 8 + 32 * s) * 2); sacc[nt] = __builtin_amdgcn_mfma_f32_16x16x32_bf16(cur.kf[s], vf, sacc[nt], 0, 0, 0); }
;             u32x2 pv; pv.x = pk2(sacc[nt][0], sacc[nt][1]); pv.y = pk2(sacc[nt][2], sacc[nt][3]);
;             *(LAS u32x2*)(lds + GC_ST + (nt * 16 + l15) * 272 + (w * 16 + quad * 4) * 2) = pv; }
	v_mfma_f32_16x16x32_bf16 v[48:51], v[108:111], v[68:71], v[48:51]
	v_mul_f32_e64 v54, v54, v138
	v_mul_f32_e64 v55, v55, v138
	v_pk_mul_f32 v[52:53], v[52:53], v[138:139] op_sel_hi:[1,0]
	v_pk_mul_f32 v[42:43], v[42:43], v[138:139] op_sel_hi:[1,0]
	s_waitcnt lgkmcnt(0)
	v_mfma_f32_16x16x32_bf16 v[48:51], v[178:181], v[44:47], v[48:51]
	v_mul_f32_e64 v40, v40, v138
	v_mul_f32_e64 v41, v41, v138
	v_pk_mul_f32 v[34:35], v[34:35], v[138:139] op_sel_hi:[1,0]
	v_pk_mul_f32 v[32:33], v[32:33], v[138:139] op_sel_hi:[1,0]
	v_mfma_f32_16x16x32_bf16 v[36:39], v[186:189], v[68:71], v[36:39]
	s_waitcnt vmcnt(10)
	v_lshlrev_b32_e32 v70, 16, v84
	v_and_b32_e32 v71, 0xffff0000, v84
	v_pk_add_f32 v[48:49], v[70:71], v[48:49] neg_lo:[0,1] neg_hi:[0,1]
	v_lshlrev_b32_e32 v70, 16, v85
	v_and_b32_e32 v71, 0xffff0000, v85
	v_pk_add_f32 v[50:51], v[70:71], v[50:51] neg_lo:[0,1] neg_hi:[0,1]
	v_cvt_pk_bf16_f32 v48, v48, v49
	v_cvt_pk_bf16_f32 v49, v50, v51
	v_add_u32_e32 v50, v155, v158
	ds_write_b64 v50, v[48:49] offset:34816
	ds_read_b128 v[48:51], v164
	v_lshl_add_u64 v[68:69], v[80:81], 0, s[0:1]
	ds_read_b128 v[80:83], v164 offset:64
	v_lshl_add_u64 v[68:69], v[68:69], 0, v[122:123]
	s_waitcnt lgkmcnt(1)
	v_mfma_f32_16x16x32_bf16 v[88:91], v[88:91], v[48:51], 0
	s_nop 0
	v_pk_mul_f32 v[26:27], v[26:27], v[138:139] op_sel_hi:[1,0]
	v_pk_mul_f32 v[24:25], v[24:25], v[138:139] op_sel_hi:[1,0]
	v_mfma_f32_16x16x32_bf16 v[214:217], v[190:193], v[44:47], v[36:39]
	v_mul_f32_e64 v78, v78, v138
	v_mul_f32_e64 v79, v79, v138
	v_pk_mul_f32 v[76:77], v[76:77], v[138:139] op_sel_hi:[1,0]
	s_nop 0
	s_nop 0
	s_nop 0
	s_nop 0
	s_nop 0
	s_nop 0
	v_mfma_f32_16x16x32_bf16 v[100:103], v[100:103], v[48:51], 0
	s_nop 0
	s_nop 0
	s_nop 0
	s_nop 0
	s_nop 0
	s_waitcnt lgkmcnt(0)
	v_mfma_f32_16x16x32_bf16 v[88:91], v[104:107], v[80:83], v[88:91]
	ds_read_b128 v[104:107], v164 offset:128
	s_nop 0
	v_mfma_f32_16x16x32_bf16 v[80:83], v[182:185], v[80:83], v[100:103]
	s_nop 0
	s_nop 1
	ds_read_b128 v[100:103], v164 offset:192
	s_waitcnt lgkmcnt(1)
	v_mfma_f32_16x16x32_bf16 v[88:91], v[108:111], v[104:107], v[88:91]
	v_mfma_f32_16x16x32_bf16 v[104:107], v[186:189], v[104:107], v[80:83]
	s_nop 2
	s_nop 0
	s_waitcnt lgkmcnt(0)
	v_mfma_f32_16x16x32_bf16 v[108:111], v[178:181], v[100:103], v[88:91]
	s_nop 0
	s_nop 0
	v_mfma_f32_16x16x32_bf16 v[178:181], v[190:193], v[100:103], v[104:107]
	s_nop 0
	s_nop 0
	s_nop 0
	s_nop 0
	s_nop 0
	v_lshlrev_b32_e32 v84, 16, v86
	v_and_b32_e32 v85, 0xffff0000, v86
	v_lshlrev_b32_e32 v86, 16, v87
	v_and_b32_e32 v87, 0xffff0000, v87
	v_pk_add_f32 v[84:85], v[84:85], v[108:109] neg_lo:[0,1] neg_hi:[0,1]
	v_pk_add_f32 v[86:87], v[86:87], v[110:111] neg_lo:[0,1] neg_hi:[0,1]
	v_cvt_pk_bf16_f32 v84, v84, v85
	v_cvt_pk_bf16_f32 v85, v86, v87
	v_add_u32_e32 v86, v155, v159
	ds_write_b64 v86, v[84:85] offset:34816
	s_waitcnt lgkmcnt(0)
	s_barrier
	ds_read_b128 v[182:185], v148 offset:34816
	ds_read_b128 v[186:189], v148 offset:34880
	ds_read_b128 v[190:193], v148 offset:37120
	ds_read_b128 v[232:235], v148 offset:37184
	v_lshl_add_u64 v[36:37], v[68:69], 0, v[114:115]
	v_lshl_add_u64 v[38:39], v[36:37], 0, s[24:25]
	v_add_co_u32_e32 v36, vcc, s38, v36
	s_nop 1
	v_addc_co_u32_e32 v37, vcc, 0, v37, vcc
	global_load_dwordx4 v[68:71], v[218:219], off
	global_load_dwordx4 v[44:47], v[218:219], off offset:64
	v_add_u32_e32 v88, s50, v154
	v_mad_i64_i32 v[88:89], s[28:29], v88, s40, v[202:203]
	v_lshl_add_u64 v[88:89], v[88:89], 0, s[0:1]
	v_lshl_add_u64 v[80:81], v[88:89], 0, v[126:127]
	v_lshl_add_u64 v[88:89], v[80:81], 0, s[26:27]
	v_add_co_u32_e32 v80, vcc, s38, v80
	s_nop 1
	v_addc_co_u32_e32 v81, vcc, 0, v81, vcc
	s_waitcnt lgkmcnt(2)
	v_mfma_f32_16x16x32_bf16 v[64:67], v[96:99], v[182:185], v[64:67]
	v_mfma_f32_16x16x32_bf16 v[64:67], v[92:95], v[186:189], v[64:67]
	s_cmp_lg_u32 s59, 0
	s_cbranch_scc1 .Lcb_skip0
	v_mfma_f32_16x16x32_bf16 v[84:87], v[194:197], v[182:185], v[198:201]
	v_mfma_f32_16x16x32_bf16 v[84:87], v[206:209], v[186:189], v[84:87]
.Lcb_skip0:
	global_load_dwordx4 v[48:51], v[36:37], off
	ds_read_b128 v[182:185], v148 offset:39424
	ds_read_b128 v[186:189], v148 offset:39488
	s_waitcnt lgkmcnt(2)
	v_mfma_f32_16x16x32_bf16 v[60:63], v[96:99], v[190:193], v[60:63]
	v_mfma_f32_16x16x32_bf16 v[60:63], v[92:95], v[232:235], v[60:63]
	s_cmp_lg_u32 s59, 0
	s_cbranch_scc1 .Lcb_skip1
	v_mfma_f32_16x16x32_bf16 v[100:103], v[194:197], v[190:193], v[210:213]
	v_mfma_f32_16x16x32_bf16 v[100:103], v[206:209], v[232:235], v[100:103]
.Lcb_skip1:
	global_load_dwordx4 v[36:39], v[38:39], off offset:64
	ds_read_b128 v[190:193], v148 offset:41728
	ds_read_b128 v[232:235], v148 offset:41792
	v_cvt_pk_bf16_f32 v218, v64, v65
	v_cvt_pk_bf16_f32 v219, v66, v67
	ds_write_b64 v169, v[218:219]
	s_waitcnt lgkmcnt(3)
	v_mfma_f32_16x16x32_bf16 v[56:59], v[96:99], v[182:185], v[56:59]
	v_mfma_f32_16x16x32_bf16 v[56:59], v[92:95], v[186:189], v[56:59]
	s_cmp_lg_u32 s59, 0
	s_cbranch_scc1 .Lcb_skip2
	v_mfma_f32_16x16x32_bf16 v[104:107], v[194:197], v[182:185], v[214:217]
	v_mfma_f32_16x16x32_bf16 v[104:107], v[206:209], v[186:189], v[104:107]
.Lcb_skip2:
	global_load_dword v123, v115, s[30:31]
	ds_read_b128 v[182:185], v148 offset:44032
	ds_read_b128 v[186:189], v148 offset:44096
	v_cvt_pk_bf16_f32 v218, v60, v61
	v_cvt_pk_bf16_f32 v219, v62, v63
	ds_write_b64 v169, v[218:219] offset:4352
	s_waitcnt lgkmcnt(4)
	v_mfma_f32_16x16x32_bf16 v[52:55], v[96:99], v[190:193], v[52:55]
	v_mfma_f32_16x16x32_bf16 v[52:55], v[92:95], v[232:235], v[52:55]
	s_cmp_lg_u32 s59, 0
	s_cbranch_scc1 .Lcb_skip3
	v_mfma_f32_16x16x32_bf16 v[108:111], v[194:197], v[190:193], v[178:181]
	v_mfma_f32_16x16x32_bf16 v[108:111], v[206:209], v[232:235], v[108:111]
.Lcb_skip3:
	global_load_dwordx4 v[80:83], v[80:81], off offset:2048
	ds_read_b128 v[190:193], v148 offset:46336
	ds_read_b128 v[232:235], v148 offset:46400
	v_cvt_pk_bf16_f32 v218, v56, v57
	v_cvt_pk_bf16_f32 v219, v58, v59
	ds_write_b64 v169, v[218:219] offset:8704
	s_waitcnt lgkmcnt(4)
	v_mfma_f32_16x16x32_bf16 v[40:43], v[96:99], v[182:185], v[40:43]
	v_mfma_f32_16x16x32_bf16 v[40:43], v[92:95], v[186:189], v[40:43]
	s_cmp_lg_u32 s59, 1
	s_cbranch_scc1 .Lcb_skip4
	v_mfma_f32_16x16x32_bf16 v[84:87], v[194:197], v[182:185], v[198:201]
	v_mfma_f32_16x16x32_bf16 v[84:87], v[206:209], v[186:189], v[84:87]
.Lcb_skip4:
	global_load_dwordx4 v[88:91], v[88:89], off offset:16
	ds_read_b128 v[182:185], v148 offset:48640
	ds_read_b128 v[186:189], v148 offset:48704
	v_cvt_pk_bf16_f32 v218, v52, v53
	v_cvt_pk_bf16_f32 v219, v54, v55
	ds_write_b64 v169, v[218:219] offset:13056
	s_waitcnt lgkmcnt(4)
	v_mfma_f32_16x16x32_bf16 v[32:35], v[96:99], v[190:193], v[32:35]
	v_mfma_f32_16x16x32_bf16 v[32:35], v[92:95], v[232:235], v[32:35]
	s_cmp_lg_u32 s59, 1
	s_cbranch_scc1 .Lcb_skip5
	v_mfma_f32_16x16x32_bf16 v[100:103], v[194:197], v[190:193], v[210:213]
	v_mfma_f32_16x16x32_bf16 v[100:103], v[206:209], v[232:235], v[100:103]
